# attention steady loop: softmax bias fed through the QK MFMA f32 C operand instead of 16 packed adds per step; bias vector refreshed only on block change or rescale
# speedup vs baseline: 1.0090x; 1.0081x over previous
.LBB0_546:
	v_lshlrev_b32_e32 v0, 1, v2
	v_and_b32_e32 v217, 32, v0
	v_lshlrev_b32_e32 v0, 4, v2
	v_and_b32_e32 v0, 0xc0, v0
	v_lshl_or_b32 v17, v190, 8, v0
	v_add_u32_e32 v0, 0, v217
	v_add3_u32 v222, v0, v216, v17
	v_max3_f32 v0, v34, v35, v18
	v_max3_f32 v2, v36, v37, v19
	s_and_b32 s0, s5, 0x3fffffc0
	v_max3_f32 v0, v0, v20, v21
	v_max3_f32 v2, v2, v40, v41
	s_lshl_b32 s0, s0, 2
	v_max3_f32 v0, v0, v38, v39
	v_max3_f32 v2, v2, v24, v25
	s_add_i32 s38, s0, 0
	v_max3_f32 v0, v0, v22, v23
	v_max3_f32 v2, v2, v44, v45
	s_mov_b32 s0, 0xff800000
	v_max3_f32 v0, v0, v42, v43
	v_max3_f32 v2, v2, v28, v29
	s_add_i32 s1, s69, 0x100
	v_max3_f32 v0, v0, v26, v27
	v_max3_f32 v2, v2, v48, v49
	s_waitcnt vmcnt(0) lgkmcnt(0)
	s_barrier
	s_mov_b64 s[2:3], 0x210000
	v_max3_f32 v0, v0, v46, v47
	v_max3_f32 v2, v2, v32, v33
	s_lshr_b32 s95, s1, 6
	v_max3_f32 v0, v0, v30, v31
	s_cmp_lg_u32 0, -1
	v_max_f32_e32 v0, v0, v2
	s_mov_b32 s93, 1
	v_mov_b32_e32 v2, v0
	s_nop 1
	v_permlane32_swap_b32_e32 v0, v2
	v_max_f32_e32 v0, v0, v2
	s_mov_b32 s10, 0
	v_cmp_neq_f32_e32 vcc, s0, v0
	v_lshlrev_b32_e32 v223, 2, v219
	v_cmp_gt_u32_e64 s[8:9], 32, v210
	v_cndmask_b32_e32 v0, 0, v0, vcc
	v_sub_f32_e32 v2, v34, v0
	v_sub_f32_e32 v3, v18, v0
	v_add_f32_e32 v221, v1, v0
	v_sub_f32_e32 v4, v35, v0
	v_sub_f32_e32 v5, v19, v0
	v_sub_f32_e32 v6, v36, v0
	s_nop 0
	v_exp_f32_e32 v82, v2
	v_exp_f32_e32 v66, v3
	v_lshl_add_u64 v[2:3], v[206:207], 0, s[2:3]
	s_mov_b32 s0, m0
	s_mov_b32 m0, s70
	s_nop 0
	global_load_lds_dwordx4 v[2:3], off
	s_mov_b32 m0, s0
	s_mov_b64 s[0:1], 0xb0000
	v_lshl_add_u64 v[2:3], v[208:209], 0, s[0:1]
	s_cselect_b32 s0, 0, 0
	s_add_i32 s0, s0, s4
	s_add_i32 s0, s0, 0x8000
	s_mov_b32 s1, m0
	s_mov_b32 m0, s0
	s_nop 0
	global_load_lds_dwordx4 v[2:3], off
	s_mov_b32 m0, s1
	ds_read_b128 v[178:181], v220 offset:8192
	ds_read_b128 v[174:177], v220 offset:8704
	ds_read_b128 v[170:173], v220 offset:10240
	ds_read_b128 v[166:169], v220 offset:10752
	ds_read_b128 v[162:165], v220 offset:12288
	ds_read_b128 v[158:161], v220 offset:12800
	ds_read_b128 v[154:157], v220 offset:14336
	ds_read_b128 v[150:153], v220 offset:14848
	v_sub_f32_e32 v7, v20, v0
	v_sub_f32_e32 v8, v37, v0
	v_sub_f32_e32 v9, v21, v0
	v_sub_f32_e32 v10, v38, v0
	v_sub_f32_e32 v11, v22, v0
	v_sub_f32_e32 v12, v39, v0
	v_sub_f32_e32 v13, v23, v0
	v_sub_f32_e32 v14, v40, v0
	v_sub_f32_e32 v15, v24, v0
	v_sub_f32_e32 v18, v41, v0
	v_sub_f32_e32 v19, v25, v0
	v_sub_f32_e32 v20, v42, v0
	v_sub_f32_e32 v21, v26, v0
	v_sub_f32_e32 v22, v43, v0
	v_sub_f32_e32 v23, v27, v0
	v_sub_f32_e32 v24, v44, v0
	v_sub_f32_e32 v25, v28, v0
	v_sub_f32_e32 v26, v45, v0
	v_sub_f32_e32 v27, v29, v0
	v_sub_f32_e32 v28, v46, v0
	v_sub_f32_e32 v29, v30, v0
	v_sub_f32_e32 v30, v47, v0
	v_sub_f32_e32 v31, v31, v0
	v_sub_f32_e32 v34, v48, v0
	v_sub_f32_e32 v32, v32, v0
	v_sub_f32_e32 v35, v49, v0
	v_sub_f32_e32 v0, v33, v0
	v_exp_f32_e32 v83, v4
	v_exp_f32_e32 v84, v6
	v_exp_f32_e32 v85, v8
	v_exp_f32_e32 v86, v10
	v_exp_f32_e32 v87, v12
	v_exp_f32_e32 v88, v14
	v_exp_f32_e32 v89, v18
	v_exp_f32_e32 v90, v20
	v_exp_f32_e32 v91, v22
	v_exp_f32_e32 v92, v24
	v_exp_f32_e32 v93, v26
	v_exp_f32_e32 v94, v28
	v_exp_f32_e32 v95, v30
	v_exp_f32_e32 v96, v34
	v_exp_f32_e32 v97, v35
	v_exp_f32_e32 v67, v5
	v_exp_f32_e32 v68, v7
	v_exp_f32_e32 v69, v9
	v_exp_f32_e32 v70, v11
	v_exp_f32_e32 v71, v13
	v_exp_f32_e32 v72, v15
	v_exp_f32_e32 v73, v19
	v_exp_f32_e32 v74, v21
	v_exp_f32_e32 v75, v23
	v_exp_f32_e32 v76, v25
	v_exp_f32_e32 v77, v27
	v_exp_f32_e32 v78, v29
	v_exp_f32_e32 v79, v31
	v_exp_f32_e32 v80, v32
	v_exp_f32_e32 v81, v0
	s_waitcnt vmcnt(2) lgkmcnt(0)
	s_barrier
	s_and_b64 vcc, exec, s[6:7]
	v_lshlrev_b32_e32 v224, 4, v190
	v_lshl_add_u32 v218, v212, 2, s38
	s_cbranch_vccnz .LBB0_562
	v_mov_b32_e32 v14, v1
	v_mov_b32_e32 v15, v1
	s_mov_b64 s[0:1], 0x370000
	v_mov_b32_e32 v0, v1
	v_mov_b32_e32 v2, v1
	v_mov_b32_e32 v3, v1
	v_mov_b32_e32 v4, v1
	v_mov_b32_e32 v5, v1
	v_mov_b32_e32 v6, v1
	v_mov_b32_e32 v7, v1
	v_mov_b32_e32 v8, v1
	v_mov_b32_e32 v9, v1
	v_mov_b32_e32 v10, v1
	v_mov_b32_e32 v11, v1
	v_mov_b32_e32 v12, v1
	v_mov_b32_e32 v13, v1
	v_mov_b64_e32 v[48:49], v[14:15]
	v_mov_b64_e32 v[32:33], v[14:15]
	s_add_i32 s4, s95, -5
	v_lshl_add_u64 v[186:187], v[208:209], 0, s[2:3]
	v_lshl_add_u64 v[188:189], v[206:207], 0, s[0:1]
	s_mov_b32 s0, 0
	s_movk_i32 s10, 0x4000
	s_movk_i32 s5, 0x2000
	v_mov_b32_e32 v50, 0
	v_mov_b64_e32 v[46:47], v[12:13]
	v_mov_b64_e32 v[44:45], v[10:11]
	v_mov_b64_e32 v[42:43], v[8:9]
	v_mov_b64_e32 v[40:41], v[6:7]
	v_mov_b64_e32 v[38:39], v[4:5]
	v_mov_b64_e32 v[36:37], v[2:3]
	v_mov_b64_e32 v[34:35], v[0:1]
	v_mov_b64_e32 v[30:31], v[12:13]
	v_mov_b64_e32 v[28:29], v[10:11]
	v_mov_b64_e32 v[26:27], v[8:9]
	v_mov_b64_e32 v[24:25], v[6:7]
	v_mov_b64_e32 v[22:23], v[4:5]
	v_mov_b64_e32 v[20:21], v[2:3]
	v_mov_b64_e32 v[18:19], v[0:1]
	s_mov_b32 s98, s93
	v_add_u32_e32 v244, s94, v223
	ds_read_b32 v244, v244
	s_lshr_b32 s98, s98, 2
	s_waitcnt lgkmcnt(0)
	v_lshrrev_b32_e32 v244, s98, v244
	v_and_b32_e32 v244, 1, v244
	v_cmp_eq_u32_e32 vcc, 1, v244
	s_nop 1
	v_cndmask_b32_e64 v228, v16, -v221, vcc
	v_mov_b32_e32 v229, v228
	v_mov_b32_e32 v230, v228
	v_mov_b32_e32 v231, v228
	v_mov_b32_e32 v232, v228
	v_mov_b32_e32 v233, v228
	v_mov_b32_e32 v234, v228
	v_mov_b32_e32 v235, v228
	v_mov_b32_e32 v236, v228
	v_mov_b32_e32 v237, v228
	v_mov_b32_e32 v238, v228
	v_mov_b32_e32 v239, v228
	v_mov_b32_e32 v240, v228
	v_mov_b32_e32 v241, v228
	v_mov_b32_e32 v242, v228
	v_mov_b32_e32 v243, v228
.LBB0_548:
	v_add_u32_e32 v0, s0, v222
	ds_read_b64_tr_b16 v[182:183], v0 offset:24576
	ds_read_b64_tr_b16 v[184:185], v0 offset:25088
	v_add_f32_e32 v2, v82, v83
	v_add_f32_e32 v2, v84, v2
	v_add_f32_e32 v2, v85, v2
	v_add_f32_e32 v2, v86, v2
	v_add_f32_e32 v2, v87, v2
	v_cvt_pk_bf16_f32 v146, v82, v83
	v_cvt_pk_bf16_f32 v147, v84, v85
	s_waitcnt lgkmcnt(9)
	v_mfma_f32_32x32x16_bf16 v[98:113], v[178:181], v[142:145], v[228:243]
	ds_read_b64_tr_b16 v[178:179], v0 offset:28672
	ds_read_b64_tr_b16 v[180:181], v0 offset:29184
	v_add_f32_e32 v2, v88, v2
	v_add_f32_e32 v2, v89, v2
	v_add_f32_e32 v2, v90, v2
	v_add_f32_e32 v2, v91, v2
	v_cvt_pk_bf16_f32 v148, v86, v87
	v_cvt_pk_bf16_f32 v149, v88, v89
	s_waitcnt lgkmcnt(10)
	v_mfma_f32_32x32x16_bf16 v[114:129], v[174:177], v[142:145], v[228:243]
	ds_read_b64_tr_b16 v[174:175], v0 offset:25600
	ds_read_b64_tr_b16 v[176:177], v0 offset:26112
	v_add_f32_e32 v2, v92, v2
	v_add_f32_e32 v2, v93, v2
	v_add_f32_e32 v2, v94, v2
	v_add_f32_e32 v2, v95, v2
	v_cvt_pk_bf16_f32 v10, v90, v91
	v_cvt_pk_bf16_f32 v11, v92, v93
	s_waitcnt lgkmcnt(11)
	v_mfma_f32_32x32x16_bf16 v[98:113], v[170:173], v[138:141], v[98:113]
	ds_read_b64_tr_b16 v[170:171], v0 offset:29696
	ds_read_b64_tr_b16 v[172:173], v0 offset:30208
	v_add_f32_e32 v2, v96, v2
	v_add_f32_e32 v2, v97, v2
	v_add_f32_e32 v2, v66, v2
	v_add_f32_e32 v2, v67, v2
	v_cvt_pk_bf16_f32 v12, v94, v95
	v_cvt_pk_bf16_f32 v13, v96, v97
	s_waitcnt lgkmcnt(12)
	v_mfma_f32_32x32x16_bf16 v[114:129], v[166:169], v[138:141], v[114:129]
	ds_read_b64_tr_b16 v[94:95], v0 offset:26624
	ds_read_b64_tr_b16 v[96:97], v0 offset:27136
	v_add_f32_e32 v2, v68, v2
	v_add_f32_e32 v2, v69, v2
	v_add_f32_e32 v2, v70, v2
	v_add_f32_e32 v2, v71, v2
	v_cvt_pk_bf16_f32 v6, v66, v67
	v_cvt_pk_bf16_f32 v7, v68, v69
	s_waitcnt lgkmcnt(13)
	v_mfma_f32_32x32x16_bf16 v[98:113], v[162:165], v[134:137], v[98:113]
	ds_read_b64_tr_b16 v[90:91], v0 offset:30720
	ds_read_b64_tr_b16 v[92:93], v0 offset:31232
	v_add_f32_e32 v2, v72, v2
	v_add_f32_e32 v2, v73, v2
	v_add_f32_e32 v2, v74, v2
	v_add_f32_e32 v2, v75, v2
	v_cvt_pk_bf16_f32 v8, v70, v71
	v_cvt_pk_bf16_f32 v9, v72, v73
	s_waitcnt lgkmcnt(14)
	v_mfma_f32_32x32x16_bf16 v[114:129], v[158:161], v[134:137], v[114:129]
	ds_read_b64_tr_b16 v[86:87], v0 offset:27648
	ds_read_b64_tr_b16 v[88:89], v0 offset:28160
	v_add_f32_e32 v2, v76, v2
	v_add_f32_e32 v2, v77, v2
	v_add_f32_e32 v2, v78, v2
	v_add_f32_e32 v14, v79, v2
	v_cvt_pk_bf16_f32 v2, v74, v75
	v_cvt_pk_bf16_f32 v3, v76, v77
	s_waitcnt lgkmcnt(14)
	v_mfma_f32_32x32x16_bf16 v[98:113], v[154:157], v[130:133], v[98:113]
	ds_read_b64_tr_b16 v[82:83], v0 offset:31744
	ds_read_b64_tr_b16 v[84:85], v0 offset:32256
	v_add_f32_e32 v0, v80, v14
	v_add_f32_e32 v0, v81, v0
	v_add_f32_e32 v51, 0, v0
	v_cvt_pk_bf16_f32 v4, v78, v79
	v_cvt_pk_bf16_f32 v5, v80, v81
	v_mfma_f32_32x32x16_bf16 v[114:129], v[150:153], v[130:133], v[114:129]
	s_mov_b32 s2, 0xfff50000
	s_mov_b32 s3, -1
	v_lshl_add_u64 v[14:15], v[188:189], 0, s[2:3]
	s_add_i32 s0, s5, s70
	s_mov_b32 s1, m0
	s_mov_b32 m0, s0
	s_nop 0
	global_load_lds_dwordx4 v[14:15], off
	s_mov_b32 m0, s1
	v_lshl_add_u64 v[14:15], v[186:187], 0, s[2:3]
	s_add_i32 s0, s10, s39
	s_mov_b32 s1, m0
	s_mov_b32 m0, s0
	s_nop 0
	global_load_lds_dwordx4 v[14:15], off
	s_mov_b32 m0, s1
	v_add_f32_e32 v192, v50, v51
	s_waitcnt lgkmcnt(0)
	v_max_f32_e32 v0, v98, v99
	v_max3_f32 v244, v100, v101, v115
	v_max3_f32 v0, v0, v114, v116
	v_max3_f32 v0, v0, v117, v102
	v_max3_f32 v244, v244, v104, v105
	v_max3_f32 v0, v0, v103, v118
	v_max3_f32 v244, v244, v120, v121
	v_max3_f32 v0, v0, v119, v106
	v_max3_f32 v244, v244, v108, v109
	v_max3_f32 v0, v0, v107, v122
	v_max3_f32 v244, v244, v124, v125
	v_max3_f32 v0, v0, v123, v110
	v_max3_f32 v244, v244, v112, v113
	v_max3_f32 v0, v0, v111, v126
	v_max3_f32 v244, v244, v128, v129
	v_max3_f32 v0, v0, v127, v244
	v_mov_b32_e32 v50, v0
	s_nop 1
	v_permlane32_swap_b32_e32 v0, v50
	v_max_f32_e32 v50, v50, v50
	v_max_f32_e32 v0, v0, v0
	v_max_f32_e32 v0, v0, v50
	v_cmp_lt_f32_e32 vcc, s71, v0
	s_cmp_lg_u64 vcc, 0
	s_cselect_b64 s[0:1], -1, 0
	s_cbranch_vccnz .LBB0_556
.LBB0_549:
	s_add_i32 s98, s93, 1
	s_and_b32 s99, s98, 3
	s_cselect_b64 s[100:101], 0, -1
	s_or_b64 s[100:101], s[100:101], s[0:1]
	s_and_b64 vcc, exec, s[100:101]
	s_cbranch_vccz .Lattn_nobias2
	v_add_u32_e32 v244, s94, v223
	ds_read_b32 v244, v244
	s_lshr_b32 s98, s98, 2
	s_waitcnt lgkmcnt(0)
	v_lshrrev_b32_e32 v244, s98, v244
	v_and_b32_e32 v244, 1, v244
	v_cmp_eq_u32_e32 vcc, 1, v244
	s_nop 1
	v_cndmask_b32_e64 v228, v16, -v221, vcc
	v_mov_b32_e32 v229, v228
	v_mov_b32_e32 v230, v228
	v_mov_b32_e32 v231, v228
	v_mov_b32_e32 v232, v228
	v_mov_b32_e32 v233, v228
	v_mov_b32_e32 v234, v228
	v_mov_b32_e32 v235, v228
	v_mov_b32_e32 v236, v228
	v_mov_b32_e32 v237, v228
	v_mov_b32_e32 v238, v228
	v_mov_b32_e32 v239, v228
	v_mov_b32_e32 v240, v228
	v_mov_b32_e32 v241, v228
	v_mov_b32_e32 v242, v228
	v_mov_b32_e32 v243, v228
.Lattn_nobias2:
	v_mfma_f32_32x32x16_bf16 v[34:49], v[146:149], v[182:185], v[34:49]
	v_exp_f32_e32 v66, v98
	v_exp_f32_e32 v67, v99
	v_exp_f32_e32 v68, v100
	v_exp_f32_e32 v69, v101
	v_mfma_f32_32x32x16_bf16 v[18:33], v[146:149], v[178:181], v[18:33]
	v_exp_f32_e32 v70, v102
	v_exp_f32_e32 v71, v103
	v_exp_f32_e32 v72, v104
	v_exp_f32_e32 v73, v105
	v_add_u32_e32 v0, s10, v220
	ds_read_b128 v[102:105], v0
	ds_read_b128 v[98:101], v0 offset:512
	v_mfma_f32_32x32x16_bf16 v[34:49], v[10:13], v[174:177], v[34:49]
	v_exp_f32_e32 v74, v106
	v_exp_f32_e32 v75, v107
	v_exp_f32_e32 v76, v108
	v_exp_f32_e32 v77, v109
	v_mfma_f32_32x32x16_bf16 v[18:33], v[10:13], v[170:173], v[18:33]
	v_exp_f32_e32 v78, v110
	v_exp_f32_e32 v79, v111
	v_exp_f32_e32 v80, v112
	v_exp_f32_e32 v81, v113
	ds_read_b128 v[166:169], v0 offset:4096
	v_mfma_f32_32x32x16_bf16 v[34:49], v[6:9], v[94:97], v[34:49]
	v_exp_f32_e32 v50, v114
	v_exp_f32_e32 v51, v115
	v_exp_f32_e32 v52, v116
	v_exp_f32_e32 v53, v117
	ds_read_b128 v[114:117], v0 offset:4608
	ds_read_b128 v[162:165], v0 offset:6144
	ds_read_b128 v[158:161], v0 offset:6656
	v_mfma_f32_32x32x16_bf16 v[18:33], v[6:9], v[90:93], v[18:33]
	v_exp_f32_e32 v54, v118
	v_exp_f32_e32 v55, v119
	v_exp_f32_e32 v56, v120
	v_exp_f32_e32 v57, v121
	v_mfma_f32_32x32x16_bf16 v[34:49], v[2:5], v[86:89], v[34:49]
	v_exp_f32_e32 v58, v122
	v_exp_f32_e32 v59, v123
	v_exp_f32_e32 v60, v124
	v_exp_f32_e32 v61, v125
	ds_read_b128 v[122:125], v0 offset:2048
	ds_read_b128 v[118:121], v0 offset:2560
	v_mfma_f32_32x32x16_bf16 v[18:33], v[2:5], v[82:85], v[18:33]
	v_exp_f32_e32 v62, v126
	v_exp_f32_e32 v63, v127
	v_exp_f32_e32 v64, v128
	v_exp_f32_e32 v65, v129
	s_waitcnt vmcnt(2) lgkmcnt(0)
	s_barrier
	s_andn2_b64 vcc, exec, s[0:1]
	v_add_u32_e32 v0, s38, v224
	s_cbranch_vccnz .LBB0_551
	s_waitcnt lgkmcnt(0)
	ds_read_b128 v[82:85], v0 offset:49248
	ds_read_b128 v[86:89], v0 offset:49216
	ds_read_b128 v[90:93], v0 offset:49184
	ds_read_b128 v[94:97], v0 offset:49152
	s_waitcnt lgkmcnt(3)
	v_pk_mul_f32 v[46:47], v[46:47], v[82:83]
	s_waitcnt lgkmcnt(2)
	v_pk_mul_f32 v[42:43], v[42:43], v[86:87]
	s_waitcnt lgkmcnt(1)
	v_pk_mul_f32 v[38:39], v[38:39], v[90:91]
	v_pk_mul_f32 v[48:49], v[48:49], v[84:85]
	v_pk_mul_f32 v[44:45], v[44:45], v[88:89]
	v_pk_mul_f32 v[40:41], v[40:41], v[92:93]
	s_waitcnt lgkmcnt(0)
	v_pk_mul_f32 v[36:37], v[36:37], v[96:97]
	v_pk_mul_f32 v[34:35], v[34:35], v[94:95]
	v_pk_mul_f32 v[30:31], v[30:31], v[82:83]
	v_pk_mul_f32 v[26:27], v[26:27], v[86:87]
	v_pk_mul_f32 v[22:23], v[22:23], v[90:91]
	v_pk_mul_f32 v[32:33], v[32:33], v[84:85]
	v_pk_mul_f32 v[28:29], v[28:29], v[88:89]
	v_pk_mul_f32 v[24:25], v[24:25], v[92:93]
	v_pk_mul_f32 v[20:21], v[20:21], v[96:97]
	v_pk_mul_f32 v[18:19], v[18:19], v[94:95]
.LBB0_551:
	s_add_i32 s0, s93, 1
	s_add_i32 s1, s10, 0x2000
	s_cmpk_lg_i32 s10, 0x4000
	s_cselect_b32 s92, s1, 0
	v_add_u32_e32 v14, s5, v222
	ds_read_b64_tr_b16 v[154:155], v14 offset:24576
	ds_read_b64_tr_b16 v[156:157], v14 offset:25088
	s_waitcnt lgkmcnt(9)
	v_mfma_f32_32x32x16_bf16 v[82:97], v[102:105], v[142:145], v[228:243]
	v_add_f32_e32 v2, v66, v67
	v_add_f32_e32 v2, v68, v2
	v_add_f32_e32 v2, v69, v2
	v_add_f32_e32 v2, v70, v2
	v_add_f32_e32 v2, v71, v2
	v_cvt_pk_bf16_f32 v146, v66, v67
	v_cvt_pk_bf16_f32 v147, v68, v69
	ds_read_b64_tr_b16 v[150:151], v14 offset:28672
	ds_read_b64_tr_b16 v[152:153], v14 offset:29184
	v_add_f32_e32 v2, v72, v2
	v_add_f32_e32 v2, v73, v2
	v_add_f32_e32 v2, v74, v2
	v_add_f32_e32 v2, v75, v2
	v_cvt_pk_bf16_f32 v148, v70, v71
	v_cvt_pk_bf16_f32 v149, v72, v73
	s_waitcnt lgkmcnt(10)
	v_mfma_f32_32x32x16_bf16 v[98:113], v[98:101], v[142:145], v[228:243]
	ds_read_b64_tr_b16 v[126:127], v14 offset:25600
	ds_read_b64_tr_b16 v[128:129], v14 offset:26112
	s_waitcnt lgkmcnt(11)
	v_mfma_f32_32x32x16_bf16 v[82:97], v[122:125], v[138:141], v[82:97]
	v_add_f32_e32 v2, v76, v2
	v_add_f32_e32 v2, v77, v2
	v_add_f32_e32 v2, v78, v2
	v_add_f32_e32 v2, v79, v2
	v_cvt_pk_bf16_f32 v10, v74, v75
	v_cvt_pk_bf16_f32 v11, v76, v77
	ds_read_b64_tr_b16 v[66:67], v14 offset:29696
	ds_read_b64_tr_b16 v[68:69], v14 offset:30208
	v_add_f32_e32 v2, v80, v2
	v_add_f32_e32 v2, v81, v2
	v_add_f32_e32 v2, v50, v2
	v_add_f32_e32 v2, v51, v2
	v_cvt_pk_bf16_f32 v12, v78, v79
	v_cvt_pk_bf16_f32 v13, v80, v81
	s_waitcnt lgkmcnt(12)
	v_mfma_f32_32x32x16_bf16 v[98:113], v[118:121], v[138:141], v[98:113]
	ds_read_b64_tr_b16 v[122:123], v14 offset:26624
	ds_read_b64_tr_b16 v[124:125], v14 offset:27136
	s_waitcnt lgkmcnt(13)
	v_mfma_f32_32x32x16_bf16 v[82:97], v[166:169], v[134:137], v[82:97]
	v_add_f32_e32 v2, v52, v2
	v_add_f32_e32 v2, v53, v2
	v_add_f32_e32 v2, v54, v2
	v_add_f32_e32 v2, v55, v2
	v_cvt_pk_bf16_f32 v6, v50, v51
	v_cvt_pk_bf16_f32 v7, v52, v53
	ds_read_b64_tr_b16 v[118:119], v14 offset:30720
	ds_read_b64_tr_b16 v[120:121], v14 offset:31232
	v_add_f32_e32 v2, v56, v2
	v_add_f32_e32 v2, v57, v2
	v_add_f32_e32 v2, v58, v2
	v_add_f32_e32 v2, v59, v2
	v_cvt_pk_bf16_f32 v8, v54, v55
	v_cvt_pk_bf16_f32 v9, v56, v57
	s_waitcnt lgkmcnt(14)
	v_mfma_f32_32x32x16_bf16 v[98:113], v[114:117], v[134:137], v[98:113]
	ds_read_b64_tr_b16 v[114:115], v14 offset:27648
	ds_read_b64_tr_b16 v[116:117], v14 offset:28160
	s_waitcnt lgkmcnt(14)
	v_mfma_f32_32x32x16_bf16 v[82:97], v[162:165], v[130:133], v[82:97]
	v_add_f32_e32 v2, v60, v2
	v_add_f32_e32 v2, v61, v2
	v_add_f32_e32 v2, v62, v2
	v_add_f32_e32 v15, v63, v2
	v_cvt_pk_bf16_f32 v2, v58, v59
	v_cvt_pk_bf16_f32 v3, v60, v61
	ds_read_b64_tr_b16 v[52:53], v14 offset:31744
	ds_read_b64_tr_b16 v[54:55], v14 offset:32256
	v_add_f32_e32 v4, v64, v15
	v_add_f32_e32 v4, v65, v4
	v_add_f32_e32 v51, 0, v4
	v_cvt_pk_bf16_f32 v4, v62, v63
	v_cvt_pk_bf16_f32 v5, v64, v65
	v_mfma_f32_32x32x16_bf16 v[98:113], v[158:161], v[130:133], v[98:113]
	s_add_i32 s1, s10, s70
	s_mov_b32 s2, m0
	s_mov_b32 m0, s1
	s_nop 0
	global_load_lds_dwordx4 v[188:189], off
	s_mov_b32 m0, s2
	s_add_i32 s1, s92, s39
	s_mov_b32 s2, m0
	s_mov_b32 m0, s1
	s_nop 0
	global_load_lds_dwordx4 v[186:187], off
	s_mov_b32 m0, s2
	s_waitcnt lgkmcnt(0)
	v_max_f32_e32 v50, v82, v83
	v_max3_f32 v62, v84, v85, v99
	v_max3_f32 v50, v50, v98, v100
	v_max3_f32 v50, v50, v101, v86
	v_max3_f32 v62, v62, v88, v89
	v_max3_f32 v50, v50, v87, v102
	v_max3_f32 v62, v62, v104, v105
	v_max3_f32 v50, v50, v103, v90
	v_max3_f32 v62, v62, v92, v93
	v_max3_f32 v50, v50, v91, v106
	v_max3_f32 v62, v62, v108, v109
	v_max3_f32 v50, v50, v107, v94
	v_max3_f32 v62, v62, v96, v97
	v_max3_f32 v63, v50, v95, v110
	v_max3_f32 v62, v62, v112, v113
	v_add_f32_e32 v50, v192, v51
	v_max3_f32 v51, v63, v111, v62
	v_mov_b32_e32 v62, v51
	s_nop 1
	v_permlane32_swap_b32_e32 v51, v62
	v_max_f32_e32 v62, v62, v62
	v_max_f32_e32 v51, v51, v51
	v_max_f32_e32 v51, v51, v62
	v_cmp_lt_f32_e32 vcc, s71, v51
	s_cmp_lg_u64 vcc, 0
	s_cselect_b64 s[0:1], -1, 0
	s_cbranch_vccnz .LBB0_559
.LBB0_552:
	v_mfma_f32_32x32x16_bf16 v[34:49], v[146:149], v[154:157], v[34:49]
	v_exp_f32_e32 v82, v82
	v_exp_f32_e32 v83, v83
	v_exp_f32_e32 v84, v84
	v_exp_f32_e32 v85, v85
	v_mfma_f32_32x32x16_bf16 v[18:33], v[146:149], v[150:153], v[18:33]
	v_exp_f32_e32 v86, v86
	v_exp_f32_e32 v87, v87
	v_exp_f32_e32 v88, v88
	v_exp_f32_e32 v89, v89
	v_add_u32_e32 v51, s92, v220
	ds_read_b128 v[178:181], v51
	ds_read_b128 v[174:177], v51 offset:512
	v_mfma_f32_32x32x16_bf16 v[34:49], v[10:13], v[126:129], v[34:49]
	v_exp_f32_e32 v90, v90
	v_exp_f32_e32 v91, v91
	v_exp_f32_e32 v92, v92
	v_exp_f32_e32 v93, v93
	ds_read_b128 v[170:173], v51 offset:2048
	ds_read_b128 v[166:169], v51 offset:2560
	v_mfma_f32_32x32x16_bf16 v[18:33], v[10:13], v[66:69], v[18:33]
	v_exp_f32_e32 v94, v94
	v_exp_f32_e32 v95, v95
	v_exp_f32_e32 v96, v96
	v_exp_f32_e32 v97, v97
	ds_read_b128 v[162:165], v51 offset:4096
	ds_read_b128 v[158:161], v51 offset:4608
	v_mfma_f32_32x32x16_bf16 v[34:49], v[6:9], v[122:125], v[34:49]
	v_exp_f32_e32 v66, v98
	v_exp_f32_e32 v67, v99
	v_exp_f32_e32 v68, v100
	v_exp_f32_e32 v69, v101
	ds_read_b128 v[154:157], v51 offset:6144
	ds_read_b128 v[150:153], v51 offset:6656
	v_mfma_f32_32x32x16_bf16 v[18:33], v[6:9], v[118:121], v[18:33]
	v_exp_f32_e32 v70, v102
	v_exp_f32_e32 v71, v103
	v_exp_f32_e32 v72, v104
	v_exp_f32_e32 v73, v105
	v_mfma_f32_32x32x16_bf16 v[34:49], v[2:5], v[114:117], v[34:49]
	v_exp_f32_e32 v74, v106
	v_exp_f32_e32 v75, v107
	v_exp_f32_e32 v76, v108
	v_exp_f32_e32 v77, v109
	v_mfma_f32_32x32x16_bf16 v[18:33], v[2:5], v[52:55], v[18:33]
	v_exp_f32_e32 v78, v110
	v_exp_f32_e32 v79, v111
	v_exp_f32_e32 v80, v112
	v_exp_f32_e32 v81, v113
	s_waitcnt vmcnt(2) lgkmcnt(0)
	s_barrier
	s_andn2_b64 vcc, exec, s[0:1]
	s_cbranch_vccnz .LBB0_554
	s_waitcnt lgkmcnt(0)
	ds_read_b128 v[52:55], v0 offset:49248
	ds_read_b128 v[56:59], v0 offset:49216
	ds_read_b128 v[60:63], v0 offset:49184
	ds_read_b128 v[98:101], v0 offset:49152
	s_waitcnt lgkmcnt(3)
	v_pk_mul_f32 v[46:47], v[46:47], v[52:53]
	s_waitcnt lgkmcnt(2)
	v_pk_mul_f32 v[42:43], v[42:43], v[56:57]
	s_waitcnt lgkmcnt(1)
	v_pk_mul_f32 v[38:39], v[38:39], v[60:61]
	v_pk_mul_f32 v[48:49], v[48:49], v[54:55]
	v_pk_mul_f32 v[44:45], v[44:45], v[58:59]
	v_pk_mul_f32 v[40:41], v[40:41], v[62:63]
	s_waitcnt lgkmcnt(0)
	v_pk_mul_f32 v[36:37], v[36:37], v[100:101]
	v_pk_mul_f32 v[34:35], v[34:35], v[98:99]
	v_pk_mul_f32 v[30:31], v[30:31], v[52:53]
	v_pk_mul_f32 v[26:27], v[26:27], v[56:57]
	v_pk_mul_f32 v[22:23], v[22:23], v[60:61]
	v_pk_mul_f32 v[32:33], v[32:33], v[54:55]
	v_pk_mul_f32 v[28:29], v[28:29], v[58:59]
	v_pk_mul_f32 v[24:25], v[24:25], v[62:63]
	v_pk_mul_f32 v[20:21], v[20:21], v[100:101]
	v_pk_mul_f32 v[18:19], v[18:19], v[98:99]

.LBB0_556:
	v_max_f32_e32 v0, v0, v0
	v_max_f32_e32 v50, 0, v0
	v_exp_f32_e64 v0, -v50
	s_and_saveexec_b64 s[2:3], s[8:9]
	ds_write_b32 v218, v0 offset:49152
	s_or_b64 exec, exec, s[2:3]
	v_sub_f32_e32 v98, v98, v50
	v_sub_f32_e32 v99, v99, v50
	v_sub_f32_e32 v100, v100, v50
	v_sub_f32_e32 v101, v101, v50
	v_sub_f32_e32 v102, v102, v50
	v_sub_f32_e32 v103, v103, v50
	v_sub_f32_e32 v104, v104, v50
	v_sub_f32_e32 v105, v105, v50
	v_sub_f32_e32 v106, v106, v50
	v_sub_f32_e32 v107, v107, v50
	v_sub_f32_e32 v108, v108, v50
	v_sub_f32_e32 v109, v109, v50
	v_sub_f32_e32 v110, v110, v50
	v_sub_f32_e32 v111, v111, v50
	v_sub_f32_e32 v112, v112, v50
	v_sub_f32_e32 v113, v113, v50
	v_sub_f32_e32 v114, v114, v50
	v_sub_f32_e32 v115, v115, v50
	v_sub_f32_e32 v116, v116, v50
	v_sub_f32_e32 v117, v117, v50
	v_sub_f32_e32 v118, v118, v50
	v_sub_f32_e32 v119, v119, v50
	v_sub_f32_e32 v120, v120, v50
	v_sub_f32_e32 v121, v121, v50
	v_sub_f32_e32 v122, v122, v50
	v_sub_f32_e32 v123, v123, v50
	v_sub_f32_e32 v124, v124, v50
	v_sub_f32_e32 v125, v125, v50
	v_sub_f32_e32 v126, v126, v50
	v_sub_f32_e32 v127, v127, v50
	v_sub_f32_e32 v128, v128, v50
	v_sub_f32_e32 v129, v129, v50
	v_add_f32_e32 v221, v221, v50
	v_mul_f32_e32 v192, v192, v0
	s_branch .LBB0_549
.LBB0_559:
	v_max_f32_e32 v51, v51, v51
	v_max_f32_e32 v62, 0, v51
	v_exp_f32_e64 v51, -v62
	s_and_saveexec_b64 s[2:3], s[8:9]
	ds_write_b32 v218, v51 offset:49152
	s_or_b64 exec, exec, s[2:3]
	v_sub_f32_e32 v82, v82, v62
	v_sub_f32_e32 v83, v83, v62
	v_sub_f32_e32 v84, v84, v62
	v_sub_f32_e32 v85, v85, v62
	v_sub_f32_e32 v86, v86, v62
	v_sub_f32_e32 v87, v87, v62
	v_sub_f32_e32 v88, v88, v62
	v_sub_f32_e32 v89, v89, v62
	v_sub_f32_e32 v90, v90, v62
	v_sub_f32_e32 v91, v91, v62
	v_sub_f32_e32 v92, v92, v62
	v_sub_f32_e32 v93, v93, v62
	v_sub_f32_e32 v94, v94, v62
	v_sub_f32_e32 v95, v95, v62
	v_sub_f32_e32 v96, v96, v62
	v_sub_f32_e32 v97, v97, v62
	v_sub_f32_e32 v98, v98, v62
	v_sub_f32_e32 v99, v99, v62
	v_sub_f32_e32 v100, v100, v62
	v_sub_f32_e32 v101, v101, v62
	v_sub_f32_e32 v102, v102, v62
	v_sub_f32_e32 v103, v103, v62
	v_sub_f32_e32 v104, v104, v62
	v_sub_f32_e32 v105, v105, v62
	v_sub_f32_e32 v106, v106, v62
	v_sub_f32_e32 v107, v107, v62
	v_sub_f32_e32 v108, v108, v62
	v_sub_f32_e32 v109, v109, v62
	v_sub_f32_e32 v110, v110, v62
	v_sub_f32_e32 v111, v111, v62
	v_sub_f32_e32 v112, v112, v62
	v_sub_f32_e32 v113, v113, v62
	v_add_f32_e32 v221, v221, v62
	v_mul_f32_e32 v50, v50, v51
	s_add_i32 s98, s93, 2
	v_add_u32_e32 v244, s94, v223
	ds_read_b32 v244, v244
	s_lshr_b32 s98, s98, 2
	s_waitcnt lgkmcnt(0)
	v_lshrrev_b32_e32 v244, s98, v244
	v_and_b32_e32 v244, 1, v244
	v_cmp_eq_u32_e32 vcc, 1, v244
	s_nop 1
	v_cndmask_b32_e64 v228, v16, -v221, vcc
	v_mov_b32_e32 v229, v228
	v_mov_b32_e32 v230, v228
	v_mov_b32_e32 v231, v228
	v_mov_b32_e32 v232, v228
	v_mov_b32_e32 v233, v228
	v_mov_b32_e32 v234, v228
	v_mov_b32_e32 v235, v228
	v_mov_b32_e32 v236, v228
	v_mov_b32_e32 v237, v228
	v_mov_b32_e32 v238, v228
	v_mov_b32_e32 v239, v228
	v_mov_b32_e32 v240, v228
	v_mov_b32_e32 v241, v228
	v_mov_b32_e32 v242, v228
	v_mov_b32_e32 v243, v228
	s_branch .LBB0_552

	.amdhsa_kernel _ZN2mk14fwd_megakernelENS_6ParamsE
		.amdhsa_group_segment_fixed_size 0
		.amdhsa_private_segment_fixed_size 0
		.amdhsa_kernarg_size 384
		.amdhsa_user_sgpr_count 2
		.amdhsa_user_sgpr_dispatch_ptr 0
		.amdhsa_user_sgpr_queue_ptr 0
		.amdhsa_user_sgpr_kernarg_segment_ptr 1
		.amdhsa_user_sgpr_dispatch_id 0
		.amdhsa_user_sgpr_kernarg_preload_length 0
		.amdhsa_user_sgpr_kernarg_preload_offset 0
		.amdhsa_user_sgpr_private_segment_size 0
		.amdhsa_uses_dynamic_stack 0
		.amdhsa_enable_private_segment 0
		.amdhsa_system_sgpr_workgroup_id_x 1
		.amdhsa_system_sgpr_workgroup_id_y 0
		.amdhsa_system_sgpr_workgroup_id_z 0
		.amdhsa_system_sgpr_workgroup_info 0
		.amdhsa_system_vgpr_workitem_id 2
		.amdhsa_next_free_vgpr 256
		.amdhsa_next_free_sgpr 102
		.amdhsa_accum_offset 256
		.amdhsa_reserve_vcc 1
		.amdhsa_float_round_mode_32 0
		.amdhsa_float_round_mode_16_64 0
		.amdhsa_float_denorm_mode_32 3
		.amdhsa_float_denorm_mode_16_64 3
		.amdhsa_dx10_clamp 1
		.amdhsa_ieee_mode 1
		.amdhsa_fp16_overflow 0
		.amdhsa_tg_split 0
		.amdhsa_exception_fp_ieee_invalid_op 0
		.amdhsa_exception_fp_denorm_src 0
		.amdhsa_exception_fp_ieee_div_zero 0
		.amdhsa_exception_fp_ieee_overflow 0
		.amdhsa_exception_fp_ieee_underflow 0
		.amdhsa_exception_fp_ieee_inexact 0
		.amdhsa_exception_int_div_zero 0
	.end_amdhsa_kernel

amdhsa.kernels:
  - .agpr_count:     0
    .args:
      - .offset:         0
        .size:           128
        .value_kind:     by_value
      - .offset:         128
        .size:           4
        .value_kind:     hidden_block_count_x
      - .offset:         132
        .size:           4
        .value_kind:     hidden_block_count_y
      - .offset:         136
        .size:           4
        .value_kind:     hidden_block_count_z
      - .offset:         140
        .size:           2
        .value_kind:     hidden_group_size_x
      - .offset:         142
        .size:           2
        .value_kind:     hidden_group_size_y
      - .offset:         144
        .size:           2
        .value_kind:     hidden_group_size_z
      - .offset:         146
        .size:           2
        .value_kind:     hidden_remainder_x
      - .offset:         148
        .size:           2
        .value_kind:     hidden_remainder_y
      - .offset:         150
        .size:           2
        .value_kind:     hidden_remainder_z
      - .offset:         168
        .size:           8
        .value_kind:     hidden_global_offset_x
      - .offset:         176
        .size:           8
        .value_kind:     hidden_global_offset_y
      - .offset:         184
        .size:           8
        .value_kind:     hidden_global_offset_z
      - .offset:         192
        .size:           2
        .value_kind:     hidden_grid_dims
      - .offset:         216
        .size:           8
        .value_kind:     hidden_multigrid_sync_arg
      - .offset:         248
        .size:           4
        .value_kind:     hidden_dynamic_lds_size
    .group_segment_fixed_size: 0
    .kernarg_segment_align: 8
    .kernarg_segment_size: 384
    .language:       OpenCL C
    .language_version:
      - 2
      - 0
    .max_flat_workgroup_size: 512
    .name:           _ZN2mk14fwd_megakernelENS_6ParamsE
    .private_segment_fixed_size: 0
    .sgpr_count:     108
    .sgpr_spill_count: 54
    .symbol:         _ZN2mk14fwd_megakernelENS_6ParamsE.kd
    .uniform_work_group_size: 1
    .uses_dynamic_stack: false
    .vgpr_count:     256
    .vgpr_spill_count: 0
    .wavefront_size: 64
